# scan phases 5-11: prep-only workgroups arrive at the grid barrier without waiting for its release (next unit's first global store waits for that generation); barrier 13-14 restored because GATES alias
# speedup vs baseline: 1.0130x; 1.0128x over previous
_Z14fwd_megakernel6Params:
	s_load_dwordx8 s[4:11], s[0:1], 0x80
	s_load_dwordx2 s[62:63], s[0:1], 0xa0
	v_writelane_b32 v250, s2, 0
	s_mov_b32 s100, 0
	v_writelane_b32 v255, s100, 26
	s_add_u32 s2, s0, 0xa0
	s_addc_u32 s3, s1, 0
	v_writelane_b32 v250, s2, 1
	v_and_b32_e32 v228, 0x3ff, v0
	s_nop 0
	v_writelane_b32 v250, s3, 2
	v_cmp_eq_u32_e64 s[2:3], 0, v228
	s_mov_b64 s[12:13], exec
	s_nop 0
	v_writelane_b32 v250, s2, 3
	s_nop 1
	v_writelane_b32 v250, s3, 4
	s_and_b64 s[2:3], s[12:13], s[2:3]
	s_mov_b64 exec, s[2:3]
	s_cbranch_execz .LBB0_2
	s_add_i32 s2, 0, 0x24000
	v_mov_b32_e32 v1, 0
	v_mov_b32_e32 v2, s2
	s_add_i32 s2, 0, 0x24004
	ds_write_b32 v2, v1
	v_mov_b32_e32 v2, s2
	s_add_i32 s2, 0, 0x24008
	ds_write_b32 v2, v1
	v_mov_b32_e32 v2, s2
	s_add_i32 s2, 0, 0x2400c
	ds_write_b32 v2, v1
	v_mov_b32_e32 v2, s2
	ds_write_b32 v2, v1

.LBB0_598:
	s_or_b64 exec, exec, s[0:1]
	s_waitcnt lgkmcnt(0)
	v_readlane_b32 s0, v255, 26
	s_nop 3
	s_cmp_eq_u32 s0, 0
	s_cbranch_scc1 .Lsb_nopend
	v_readlane_b32 s22, v251, 13
	v_readlane_b32 s23, v251, 14
	s_mov_b32 s1, 0
	v_mov_b32_e32 v2, 0
	s_nop 3
.Lsb_poll_b:
	global_load_dword v3, v2, s[22:23] sc1
	s_add_i32 s1, s1, 1
	s_waitcnt vmcnt(0)
	v_subrev_u32_e32 v3, s0, v3
	v_cmp_gt_i32_e32 vcc, 0, v3
	s_cbranch_vccz .Lsb_done_b
	s_cmp_lt_u32 s1, 0x100000
	s_cbranch_scc1 .Lsb_poll_b
.Lsb_done_b:
	s_mov_b32 s0, 0
	v_writelane_b32 v255, s0, 26
.Lsb_nopend:
	s_barrier
	ds_read_b32 v0, v158
	v_ashrrev_i32_e32 v51, 6, v148
	v_and_b32_e32 v52, 31, v148
	v_and_b32_e32 v59, 1, v51
	v_lshrrev_b32_e32 v53, 5, v160
	v_lshl_or_b32 v55, v59, 5, v52
	v_ashrrev_i32_e32 v60, 7, v148
	v_cmp_ne_u32_e64 s[44:45], 1, v51
	v_mov_b32_e32 v2, 0
	v_lshlrev_b32_e32 v54, 4, v53
	v_mul_u32_u24_e32 v18, 0x110, v55
	v_mov_b32_e32 v3, 0
	v_mov_b32_e32 v4, 0
	v_mov_b32_e32 v5, 0
	v_mov_b32_e32 v6, 0
	v_mov_b32_e32 v7, 0
	v_mov_b32_e32 v8, 0
	v_mov_b32_e32 v9, 0
	v_mov_b32_e32 v10, 0
	v_mov_b32_e32 v11, 0
	v_mov_b32_e32 v12, 0
	v_mov_b32_e32 v13, 0
	v_mov_b32_e32 v14, 0
	v_mov_b32_e32 v15, 0
	v_mov_b32_e32 v16, 0
	v_mov_b32_e32 v17, 0
	s_and_saveexec_b64 s[0:1], s[44:45]
	s_cbranch_execz .LBB0_600
	v_lshl_or_b32 v2, v60, 5, v52
	v_mul_lo_u32 v2, v2, s14
	v_add3_u32 v10, v146, v2, v54
	v_add3_u32 v11, v146, v18, v54
	ds_read_b128 v[2:5], v10 offset:17408
	ds_read_b128 v[20:23], v10 offset:17440
	ds_read_b128 v[6:9], v11 offset:17408
	ds_read_b128 v[24:27], v11 offset:17440
	ds_read_b128 v[28:31], v10 offset:17472
	ds_read_b128 v[32:35], v10 offset:17504
	ds_read_b128 v[36:39], v11 offset:17472
	ds_read_b128 v[40:43], v11 offset:17504
	ds_read_b128 v[44:47], v10 offset:17536
	ds_read_b128 v[62:65], v10 offset:17568
	ds_read_b128 v[66:69], v11 offset:17536
	ds_read_b128 v[70:73], v11 offset:17568
	ds_read_b128 v[74:77], v10 offset:17600
	ds_read_b128 v[78:81], v10 offset:17632
	ds_read_b128 v[82:85], v11 offset:17600
	ds_read_b128 v[86:89], v11 offset:17632
	s_waitcnt lgkmcnt(13)
	v_mfma_f32_32x32x16_bf16 v[2:17], v[2:5], v[6:9], 0
	s_waitcnt lgkmcnt(12)
	v_mfma_f32_32x32x16_bf16 v[2:17], v[20:23], v[24:27], v[2:17]
	s_waitcnt lgkmcnt(9)
	v_mfma_f32_32x32x16_bf16 v[2:17], v[28:31], v[36:39], v[2:17]
	s_waitcnt lgkmcnt(8)
	v_mfma_f32_32x32x16_bf16 v[2:17], v[32:35], v[40:43], v[2:17]
	s_waitcnt lgkmcnt(5)
	v_mfma_f32_32x32x16_bf16 v[2:17], v[44:47], v[66:69], v[2:17]
	s_waitcnt lgkmcnt(4)
	v_mfma_f32_32x32x16_bf16 v[2:17], v[62:65], v[70:73], v[2:17]
	s_waitcnt lgkmcnt(1)
	v_mfma_f32_32x32x16_bf16 v[2:17], v[74:77], v[82:85], v[2:17]
	s_waitcnt lgkmcnt(0)
	v_mfma_f32_32x32x16_bf16 v[2:17], v[78:81], v[86:89], v[2:17]

.LBB0_769:
	v_readlane_b32 s16, v255, 26
	s_nop 3
	s_cmp_eq_u32 s16, 0
	s_cbranch_scc1 .Lsb_arr
	v_readlane_b32 s24, v251, 13
	v_readlane_b32 s25, v251, 14
	s_mov_b32 s17, 0
	s_nop 3
.Lsb_poll_a:
	global_load_dword v4, v1, s[24:25] sc1
	s_add_i32 s17, s17, 1
	s_waitcnt vmcnt(0)
	v_subrev_u32_e32 v4, s16, v4
	v_cmp_gt_i32_e32 vcc, 0, v4
	s_cbranch_vccz .Lsb_done_a
	s_cmp_lt_u32 s17, 0x100000
	s_cbranch_scc1 .Lsb_poll_a
.Lsb_done_a:
	s_mov_b32 s16, 0
	v_writelane_b32 v255, s16, 26

.LBB0_771:
	s_or_b64 exec, exec, s[22:23]
	v_cvt_f32_u32_e32 v5, v3
	s_waitcnt vmcnt(0)
	v_readfirstlane_b32 s2, v4
	v_sub_u32_e32 v4, 0, v3
	v_rcp_iflag_f32_e32 v5, v5
	v_add_u32_e32 v6, s2, v0
	v_mul_f32_e32 v5, 0x4f7ffffe, v5
	v_cvt_u32_f32_e32 v5, v5
	v_mul_lo_u32 v0, v4, v5
	v_mul_hi_u32 v0, v5, v0
	v_add_u32_e32 v0, v5, v0
	v_mul_hi_u32 v0, v6, v0
	v_mul_lo_u32 v4, v0, v3
	v_sub_u32_e32 v4, v6, v4
	v_add_u32_e32 v5, 1, v0
	v_cmp_ge_u32_e32 vcc, v4, v3
	s_nop 1
	v_cndmask_b32_e32 v0, v0, v5, vcc
	v_sub_u32_e32 v5, v4, v3
	v_cndmask_b32_e32 v4, v4, v5, vcc
	v_add_u32_e32 v5, 1, v0
	v_cmp_ge_u32_e32 vcc, v4, v3
	v_add_u32_e32 v4, 1, v6
	s_nop 0
	v_cndmask_b32_e32 v0, v0, v5, vcc
	v_mul_lo_u32 v5, v3, v0
	v_add_u32_e32 v3, v5, v3
	v_cmp_ne_u32_e32 vcc, v4, v3
	s_and_saveexec_b64 s[16:17], vcc
	s_xor_b64 s[22:23], exec, s[16:17]
	s_cbranch_execz .LBB0_785
	v_readlane_b32 s16, v250, 0
	v_readlane_b32 s17, v254, 38
	s_nop 3
	s_cmp_lt_u32 s16, 0x80
	s_cbranch_scc1 .Lsb_wait_n
	s_cmp_lt_u32 s17, 6
	s_cbranch_scc1 .Lsb_wait_n
	s_cmp_gt_u32 s17, 12
	s_cbranch_scc1 .Lsb_wait_n
	v_add_u32_e32 v4, 1, v0
	s_nop 0
	v_readfirstlane_b32 s16, v4
	s_nop 3
	v_writelane_b32 v255, s16, 26
	s_branch .LBB0_785
.Lsb_wait_n:
	v_readlane_b32 s16, v251, 13
	v_readlane_b32 s17, v251, 14
	s_waitcnt lgkmcnt(0)
	s_nop 3
	global_load_dword v2, v1, s[16:17] sc1
	s_waitcnt vmcnt(0)
	v_cmp_eq_u32_e32 vcc, v2, v0
	s_and_saveexec_b64 s[26:27], vcc
	s_cbranch_execz .LBB0_784
	s_mov_b32 s2, 1
	s_mov_b64 s[30:31], 0
	s_branch .LBB0_775

.LBB0_788:
	s_or_b64 exec, exec, s[26:27]
	s_waitcnt vmcnt(0)
	v_readfirstlane_b32 s2, v3
	v_sub_u32_e32 v4, 0, v2
	v_readlane_b32 s16, v251, 13
	v_add_u32_e32 v3, s2, v0
	v_cvt_f32_u32_e32 v0, v2
	v_readlane_b32 s17, v251, 14
	s_mov_b64 s[26:27], -1
	v_rcp_iflag_f32_e32 v0, v0
	s_nop 0
	v_mul_f32_e32 v0, 0x4f7ffffe, v0
	v_cvt_u32_f32_e32 v0, v0
	v_mul_lo_u32 v4, v4, v0
	v_mul_hi_u32 v4, v0, v4
	v_add_u32_e32 v0, v0, v4
	v_mul_hi_u32 v0, v3, v0
	v_mul_lo_u32 v4, v0, v2
	v_sub_u32_e32 v4, v3, v4
	v_cmp_ge_u32_e32 vcc, v4, v2
	v_add_u32_e32 v5, 1, v0
	v_add_u32_e32 v3, 1, v3
	v_cndmask_b32_e32 v0, v0, v5, vcc
	v_sub_u32_e32 v5, v4, v2
	v_cndmask_b32_e32 v4, v4, v5, vcc
	v_cmp_ge_u32_e32 vcc, v4, v2
	v_add_u32_e32 v4, 1, v0
	s_nop 0
	v_cndmask_b32_e32 v0, v0, v4, vcc
	v_mul_lo_u32 v4, v2, v0
	v_add_u32_e32 v2, v4, v2
	v_cmp_ne_u32_e32 vcc, v3, v2
	v_mov_b64_e32 v[2:3], s[16:17]
	s_and_saveexec_b64 s[22:23], vcc
	s_cbranch_execz .LBB0_800
	v_readlane_b32 s16, v250, 0
	v_readlane_b32 s17, v254, 38
	s_nop 3
	s_cmp_lt_u32 s16, 0x80
	s_cbranch_scc1 .Lsb_wait_l1
	s_cmp_lt_u32 s17, 6
	s_cbranch_scc1 .Lsb_wait_l1
	s_cmp_gt_u32 s17, 12
	s_cbranch_scc1 .Lsb_wait_l1
	s_mov_b64 s[26:27], 0
	s_branch .LBB0_800
.Lsb_wait_l1:
	v_readlane_b32 s16, v251, 13
	v_readlane_b32 s17, v251, 14
	s_mov_b64 s[30:31], 0
	s_nop 3
	global_load_dword v2, v1, s[16:17] sc1
	s_waitcnt vmcnt(0)
	v_cmp_eq_u32_e32 vcc, v2, v0
	s_and_saveexec_b64 s[26:27], vcc
	s_cbranch_execz .LBB0_799
	s_mov_b32 s2, 1
	s_branch .LBB0_792

.LBB0_802:
	s_or_b64 exec, exec, s[22:23]
	v_readlane_b32 s16, v250, 0
	v_readlane_b32 s17, v254, 38
	s_nop 3
	s_cmp_lt_u32 s16, 0x80
	s_cbranch_scc1 .Lsb_wait_l2
	s_cmp_lt_u32 s17, 6
	s_cbranch_scc1 .Lsb_wait_l2
	s_cmp_gt_u32 s17, 12
	s_cbranch_scc1 .Lsb_wait_l2
	v_add_u32_e32 v4, 1, v0
	s_nop 0
	v_readfirstlane_b32 s16, v4
	s_nop 3
	v_writelane_b32 v255, s16, 26
	s_branch .LBB0_805
.Lsb_wait_l2:
	s_mov_b64 s[22:23], exec
	v_mbcnt_lo_u32_b32 v0, s22, 0
	v_mbcnt_hi_u32_b32 v0, s23, v0
	v_cmp_eq_u32_e32 vcc, 0, v0
	s_waitcnt vmcnt(0)
	buffer_inv sc1
	s_and_saveexec_b64 s[26:27], vcc
	s_cbranch_execz .LBB0_804
	s_bcnt1_i32_b64 s2, s[22:23]
	v_readlane_b32 s16, v251, 9
	v_mov_b32_e32 v0, s2
	v_readlane_b32 s17, v251, 10
	s_nop 4
	global_atomic_add v1, v0, s[16:17]
